# code placement: conv-gate K-loop head at byte phase 12 mod 64 (others 16 / 12)
# baseline (speedup 1.0000x reference)
; #define PG8_STAGE(bufoff, gbase, voff) do { _Pragma("unroll") for (int _i = 0; _i < 2; ++_i) \
;         __builtin_amdgcn_global_load_lds((const unsigned*)((const char*)(gbase) + (voff)[_i]), (LAS unsigned*)(lds + (bufoff) + ldsw + _i * 8192), 16, 0, 0); } while (0)
; #define PG8_LDA(dst, b, h) do { _Pragma("unroll") for (int m = 0; m < 4; ++m) _Pragma("unroll") for (int k = 0; k < 2; ++k) dst[m][k] = *(const LAS bf16x8*)(lds + PG8_SA(b, h) + aoff + m * 2048 + k * 1024); } while (0)
; #define PG8_LDB(dst, b, h) do { _Pragma("unroll") for (int n = 0; n < 2; ++n) _Pragma("unroll") for (int k = 0; k < 2; ++k) dst[n][k] = *(const LAS bf16x8*)(lds + PG8_SB(b, h) + boff + n * 2048 + k * 1024); } while (0)
; #define PG8_MMA(ai, bj, At, Bt) do { __builtin_amdgcn_s_setprio(1); _Pragma("unroll") for (int m = 0; m < 4; ++m) _Pragma("unroll") for (int n = 0; n < 2; ++n) _Pragma("unroll") for (int k = 0; k < 2; ++k) \
;         acc[ai][bj][m][n] = __builtin_amdgcn_mfma_f32_16x16x32_bf16(Bt[n][k], At[m][k], acc[ai][bj][m][n], 0, 0, 0); __builtin_amdgcn_s_setprio(0); } while (0)
; #define PG8_WAIT_V(n) asm volatile("s_waitcnt vmcnt(" #n ")" ::: "memory")
; #define PG8_WAIT_L(n) asm volatile("s_waitcnt lgkmcnt(" #n ")" ::: "memory")
; #define PG8_BAR __builtin_amdgcn_s_barrier()
; #define PG8_SCHED __builtin_amdgcn_sched_barrier(0)
;     ...
;         const bool has_next = S.next(ui + 1, nxt);
;         const char* nA = has_next ? nxt.A : cA; const char* nB = has_next ? nxt.B : cB;
;         for (int t = 0; t < nt; t += 2) {
;             const bool last = (t == nt - 2);
;             const char* a1 = cA + (size_t)(t + 1) * kstep;
;             const char* a2 = last ? nA : cA + (size_t)(t + 2) * kstep; const char* b2 = last ? nB : cB + (size_t)(t + 2) * kstep;
;             const char* a3 = a2 + kstep; const char* b3 = b2 + kstep;
;             PG8_LDB(B0, 0, 0); PG8_LDB(B1, 0, 1); PG8_SCHED; PG8_LDA(At, 0, 0); PG8_STAGE(PG8_SA(1, 1), a1 + hstepA, voffA);
;             PG8_WAIT_V(8); PG8_WAIT_L(0); PG8_BAR; PG8_MMA(0, 0, At, B0); PG8_MMA(0, 1, At, B1); PG8_BAR; PG8_SCHED;
;             PG8_LDA(At, 0, 1); PG8_STAGE(PG8_SB(0, 0), b2, voffB); PG8_STAGE(PG8_SB(0, 1), b2 + hstepB, voffB); PG8_STAGE(PG8_SA(0, 0), a2, voffA);
;             PG8_WAIT_V(8); PG8_WAIT_L(0); PG8_BAR; PG8_MMA(1, 0, At, B0); PG8_MMA(1, 1, At, B1); PG8_BAR; PG8_SCHED;
.LBB0_158:
	s_mov_b64 s[56:57], s[18:19]
	s_mov_b64 s[16:17], s[2:3]
	v_mov_b32_e32 v228, v128
	s_xor_b64 s[2:3], s[36:37], -1
	v_mov_b32_e32 v128, s57
	s_and_b64 s[0:1], s[36:37], exec
	v_cndmask_b32_e64 v132, v189, v128, s[36:37]
	v_mov_b32_e32 v128, s56
	s_mov_b64 s[68:69], s[8:9]
	s_mov_b64 s[54:55], s[40:41]
	s_cselect_b32 s18, s17, s13
	s_cselect_b32 s19, s16, s12
	v_cndmask_b32_e64 v133, v188, v128, s[36:37]
	s_mov_b32 s8, 0
	s_mov_b64 s[0:1], 0x100
	v_mov_b64_e32 v[128:129], v[202:203]
	v_mov_b64_e32 v[130:131], v[200:201]
	s_nop 0
	s_nop 0
	s_nop 0
	s_nop 0
	s_nop 0
	s_nop 0
	s_nop 0
	s_nop 0
	s_nop 0
	s_nop 0
.LBB0_159:
	s_add_i32 s38, s8, 2
	s_add_u32 s26, s12, s0
	s_addc_u32 s9, s13, s1
	s_add_i32 s27, 0, 0x10000
	s_cmp_eq_u32 s63, s8
	s_cselect_b32 s9, s18, s9
	s_cselect_b32 s8, s19, s26
	s_cselect_b64 vcc, -1, 0
	s_add_i32 s26, 0, 0x14000
	v_lshl_add_u64 v[150:151], v[188:189], 0, s[0:1]
	v_add_u32_e32 v146, s27, v226
	v_add_u32_e32 v162, s26, v226
	ds_read_b128 v[134:137], v146
	ds_read_b128 v[138:141], v146 offset:1024
	ds_read_b128 v[142:145], v146 offset:2048
	ds_read_b128 v[146:149], v146 offset:3072
	v_cndmask_b32_e32 v205, v151, v132, vcc
	v_cndmask_b32_e32 v204, v150, v133, vcc
	ds_read_b128 v[150:153], v162
	ds_read_b128 v[154:157], v162 offset:1024
	ds_read_b128 v[158:161], v162 offset:2048
	ds_read_b128 v[162:165], v162 offset:3072
	v_lshl_add_u64 v[212:213], s[12:13], 0, v[130:131]
	s_add_i32 m0, s20, 0xc000
	ds_read_b128 v[166:169], v227
	ds_read_b128 v[170:173], v227 offset:1024
	ds_read_b128 v[174:177], v227 offset:2048
	ds_read_b128 v[178:181], v227 offset:3072
	ds_read_b128 v[230:233], v227 offset:4096
	ds_read_b128 v[234:237], v227 offset:5120
	ds_read_b128 v[238:241], v227 offset:6144
	ds_read_b128 v[242:245], v227 offset:7168
	global_load_lds_dwordx4 v[212:213], off
	v_lshl_add_u64 v[212:213], s[12:13], 0, v[128:129]
	s_add_i32 m0, s20, 0xe000
	s_nop 0
	global_load_lds_dwordx4 v[212:213], off
	s_waitcnt vmcnt(8)
	s_waitcnt lgkmcnt(0)
	s_barrier
	s_setprio 1
	s_waitcnt lgkmcnt(0)
	v_mfma_f32_16x16x32_bf16 v[124:127], v[134:137], v[166:169], v[124:127]
	v_mfma_f32_16x16x32_bf16 v[0:3], v[142:145], v[166:169], v[0:3]
	v_mfma_f32_16x16x32_bf16 v[120:123], v[134:137], v[174:177], v[120:123]
	v_mfma_f32_16x16x32_bf16 v[116:119], v[142:145], v[174:177], v[116:119]
	v_mfma_f32_16x16x32_bf16 v[112:115], v[134:137], v[230:233], v[112:115]
	v_mfma_f32_16x16x32_bf16 v[108:111], v[142:145], v[230:233], v[108:111]
	v_mfma_f32_16x16x32_bf16 v[104:107], v[134:137], v[238:241], v[104:107]
	v_mfma_f32_16x16x32_bf16 v[4:7], v[142:145], v[238:241], v[4:7]
	v_mfma_f32_16x16x32_bf16 v[124:127], v[138:141], v[170:173], v[124:127]
	v_mfma_f32_16x16x32_bf16 v[0:3], v[146:149], v[170:173], v[0:3]
	v_mfma_f32_16x16x32_bf16 v[120:123], v[138:141], v[178:181], v[120:123]
	v_mfma_f32_16x16x32_bf16 v[116:119], v[146:149], v[178:181], v[116:119]
	v_mfma_f32_16x16x32_bf16 v[112:115], v[138:141], v[234:237], v[112:115]
	v_mfma_f32_16x16x32_bf16 v[108:111], v[146:149], v[234:237], v[108:111]
	v_mfma_f32_16x16x32_bf16 v[104:107], v[138:141], v[242:245], v[104:107]
	v_mfma_f32_16x16x32_bf16 v[4:7], v[146:149], v[242:245], v[4:7]
	s_setprio 0
	s_setprio 1
	v_mfma_f32_16x16x32_bf16 v[100:103], v[150:153], v[166:169], v[100:103]
	v_mfma_f32_16x16x32_bf16 v[96:99], v[158:161], v[166:169], v[96:99]
	v_mfma_f32_16x16x32_bf16 v[92:95], v[150:153], v[174:177], v[92:95]
	v_mfma_f32_16x16x32_bf16 v[88:91], v[158:161], v[174:177], v[88:91]
	v_mfma_f32_16x16x32_bf16 v[84:87], v[150:153], v[230:233], v[84:87]
	v_mfma_f32_16x16x32_bf16 v[80:83], v[158:161], v[230:233], v[80:83]
	v_mfma_f32_16x16x32_bf16 v[76:79], v[150:153], v[238:241], v[76:79]
	v_mfma_f32_16x16x32_bf16 v[72:75], v[158:161], v[238:241], v[72:75]
	v_mfma_f32_16x16x32_bf16 v[100:103], v[154:157], v[170:173], v[100:103]
	v_mfma_f32_16x16x32_bf16 v[96:99], v[162:165], v[170:173], v[96:99]
	v_mfma_f32_16x16x32_bf16 v[92:95], v[154:157], v[178:181], v[92:95]
	v_mfma_f32_16x16x32_bf16 v[88:91], v[162:165], v[178:181], v[88:91]
	v_mfma_f32_16x16x32_bf16 v[84:87], v[154:157], v[234:237], v[84:87]
	v_mfma_f32_16x16x32_bf16 v[80:83], v[162:165], v[234:237], v[80:83]
	v_mfma_f32_16x16x32_bf16 v[76:79], v[154:157], v[242:245], v[76:79]
	v_mfma_f32_16x16x32_bf16 v[72:75], v[162:165], v[242:245], v[72:75]
	s_setprio 0
	s_barrier
	s_add_i32 s27, s27, s11
	v_lshl_add_u64 v[212:213], v[204:205], 0, v[192:193]
	s_mov_b32 m0, s27
	ds_read_b128 v[166:169], v227 offset:16384
	ds_read_b128 v[170:173], v227 offset:17408
	ds_read_b128 v[174:177], v227 offset:18432
	ds_read_b128 v[178:181], v227 offset:19456
	ds_read_b128 v[230:233], v227 offset:20480
	ds_read_b128 v[234:237], v227 offset:21504
	ds_read_b128 v[238:241], v227 offset:22528
	ds_read_b128 v[242:245], v227 offset:23552
	global_load_lds_dwordx4 v[212:213], off
	v_lshl_add_u64 v[218:219], v[204:205], 0, v[196:197]
	s_add_i32 m0, s27, 0x2000
	v_lshl_add_u64 v[204:205], v[204:205], 0, v[198:199]
	s_add_i32 s26, s26, s11
	global_load_lds_dwordx4 v[218:219], off
	v_lshl_add_u64 v[246:247], v[204:205], 0, v[192:193]
	s_mov_b32 m0, s26
	v_lshl_add_u64 v[204:205], v[204:205], 0, v[196:197]
	global_load_lds_dwordx4 v[246:247], off
	s_add_i32 m0, s26, 0x2000
	v_lshl_add_u64 v[248:249], s[8:9], 0, v[190:191]
	global_load_lds_dwordx4 v[204:205], off
	s_mov_b32 m0, s20
	v_lshl_add_u64 v[250:251], s[8:9], 0, v[194:195]
	global_load_lds_dwordx4 v[248:249], off
	s_mov_b32 m0, s48
	s_nop 0
	global_load_lds_dwordx4 v[250:251], off
	s_waitcnt vmcnt(8)
	s_waitcnt lgkmcnt(0)
	s_barrier
; #define PG8_STAGE(bufoff, gbase, voff) do { _Pragma("unroll") for (int _i = 0; _i < 2; ++_i) \
;         __builtin_amdgcn_global_load_lds((const unsigned*)((const char*)(gbase) + (voff)[_i]), (LAS unsigned*)(lds + (bufoff) + ldsw + _i * 8192), 16, 0, 0); } while (0)
; #define PG8_LDA(dst, b, h) do { _Pragma("unroll") for (int m = 0; m < 4; ++m) _Pragma("unroll") for (int k = 0; k < 2; ++k) dst[m][k] = *(const LAS bf16x8*)(lds + PG8_SA(b, h) + aoff + m * 2048 + k * 1024); } while (0)
; #define PG8_LDB(dst, b, h) do { _Pragma("unroll") for (int n = 0; n < 2; ++n) _Pragma("unroll") for (int k = 0; k < 2; ++k) dst[n][k] = *(const LAS bf16x8*)(lds + PG8_SB(b, h) + boff + n * 2048 + k * 1024); } while (0)
; #define PG8_MMA(ai, bj, At, Bt) do { __builtin_amdgcn_s_setprio(1); _Pragma("unroll") for (int m = 0; m < 4; ++m) _Pragma("unroll") for (int n = 0; n < 2; ++n) _Pragma("unroll") for (int k = 0; k < 2; ++k) \
;         acc[ai][bj][m][n] = __builtin_amdgcn_mfma_f32_16x16x32_bf16(Bt[n][k], At[m][k], acc[ai][bj][m][n], 0, 0, 0); __builtin_amdgcn_s_setprio(0); } while (0)
; #define PG8_WAIT_V(n) asm volatile("s_waitcnt vmcnt(" #n ")" ::: "memory")
; #define PG8_WAIT_L(n) asm volatile("s_waitcnt lgkmcnt(" #n ")" ::: "memory")
; #define PG8_BAR __builtin_amdgcn_s_barrier()
; #define PG8_SCHED __builtin_amdgcn_sched_barrier(0)
;     ...
;             PG8_WAIT_V(8); PG8_WAIT_L(0); PG8_BAR; PG8_MMA(1, 0, At, B0); PG8_MMA(1, 1, At, B1); PG8_BAR; PG8_SCHED;
;             PG8_LDB(B0, 1, 0); PG8_LDB(B1, 1, 1); PG8_SCHED; PG8_LDA(At, 1, 0); PG8_STAGE(PG8_SA(0, 1), a2 + hstepA, voffA);
;             PG8_WAIT_V(8); PG8_WAIT_L(0); PG8_BAR; PG8_MMA(0, 0, At, B0); PG8_MMA(0, 1, At, B1); PG8_BAR; PG8_SCHED;
	s_setprio 1
	s_waitcnt lgkmcnt(0)
	v_mfma_f32_16x16x32_bf16 v[68:71], v[134:137], v[166:169], v[68:71]
	v_mfma_f32_16x16x32_bf16 v[8:11], v[142:145], v[166:169], v[8:11]
	v_mfma_f32_16x16x32_bf16 v[64:67], v[134:137], v[174:177], v[64:67]
	v_mfma_f32_16x16x32_bf16 v[60:63], v[142:145], v[174:177], v[60:63]
	v_mfma_f32_16x16x32_bf16 v[56:59], v[134:137], v[230:233], v[56:59]
	v_mfma_f32_16x16x32_bf16 v[52:55], v[142:145], v[230:233], v[52:55]
	v_mfma_f32_16x16x32_bf16 v[48:51], v[134:137], v[238:241], v[48:51]
	v_mfma_f32_16x16x32_bf16 v[12:15], v[142:145], v[238:241], v[12:15]
	v_mfma_f32_16x16x32_bf16 v[68:71], v[138:141], v[170:173], v[68:71]
	v_mfma_f32_16x16x32_bf16 v[8:11], v[146:149], v[170:173], v[8:11]
	v_mfma_f32_16x16x32_bf16 v[64:67], v[138:141], v[178:181], v[64:67]
	v_mfma_f32_16x16x32_bf16 v[60:63], v[146:149], v[178:181], v[60:63]
	v_mfma_f32_16x16x32_bf16 v[56:59], v[138:141], v[234:237], v[56:59]
	v_mfma_f32_16x16x32_bf16 v[52:55], v[146:149], v[234:237], v[52:55]
	v_mfma_f32_16x16x32_bf16 v[48:51], v[138:141], v[242:245], v[48:51]
	v_mfma_f32_16x16x32_bf16 v[12:15], v[146:149], v[242:245], v[12:15]
	s_setprio 0
	s_setprio 1
	v_mfma_f32_16x16x32_bf16 v[44:47], v[150:153], v[166:169], v[44:47]
	v_mfma_f32_16x16x32_bf16 v[40:43], v[158:161], v[166:169], v[40:43]
	v_mfma_f32_16x16x32_bf16 v[36:39], v[150:153], v[174:177], v[36:39]
	v_mfma_f32_16x16x32_bf16 v[32:35], v[158:161], v[174:177], v[32:35]
	v_mfma_f32_16x16x32_bf16 v[28:31], v[150:153], v[230:233], v[28:31]
	v_mfma_f32_16x16x32_bf16 v[24:27], v[158:161], v[230:233], v[24:27]
	v_mfma_f32_16x16x32_bf16 v[20:23], v[150:153], v[238:241], v[20:23]
	v_mfma_f32_16x16x32_bf16 v[16:19], v[158:161], v[238:241], v[16:19]
	v_mfma_f32_16x16x32_bf16 v[44:47], v[154:157], v[170:173], v[44:47]
	v_mfma_f32_16x16x32_bf16 v[40:43], v[162:165], v[170:173], v[40:43]
	v_mfma_f32_16x16x32_bf16 v[36:39], v[154:157], v[178:181], v[36:39]
	v_mfma_f32_16x16x32_bf16 v[32:35], v[162:165], v[178:181], v[32:35]
	v_mfma_f32_16x16x32_bf16 v[28:31], v[154:157], v[234:237], v[28:31]
	v_mfma_f32_16x16x32_bf16 v[24:27], v[162:165], v[234:237], v[24:27]
	v_mfma_f32_16x16x32_bf16 v[20:23], v[154:157], v[242:245], v[20:23]
	v_mfma_f32_16x16x32_bf16 v[16:19], v[162:165], v[242:245], v[16:19]
	s_setprio 0
	s_barrier
	s_add_i32 s26, 0, 0x18000
	s_add_i32 s27, 0, 0x1c000
	v_add_u32_e32 v146, s26, v226
	v_add_u32_e32 v162, s27, v226
	ds_read_b128 v[134:137], v146
	ds_read_b128 v[138:141], v146 offset:1024
	ds_read_b128 v[142:145], v146 offset:2048
	ds_read_b128 v[146:149], v146 offset:3072
	ds_read_b128 v[150:153], v162
	ds_read_b128 v[154:157], v162 offset:1024
	ds_read_b128 v[158:161], v162 offset:2048
	ds_read_b128 v[162:165], v162 offset:3072
	s_add_u32 s8, s8, s10
	s_addc_u32 s9, s9, 0
	s_mov_b32 m0, s51
	v_lshl_add_u64 v[214:215], s[8:9], 0, v[190:191]
	ds_read_b128 v[166:169], v227 offset:32768
	ds_read_b128 v[170:173], v227 offset:33792
	ds_read_b128 v[174:177], v227 offset:34816
	ds_read_b128 v[178:181], v227 offset:35840
	ds_read_b128 v[230:233], v227 offset:36864
	ds_read_b128 v[234:237], v227 offset:37888
	ds_read_b128 v[238:241], v227 offset:38912
	ds_read_b128 v[242:245], v227 offset:39936
	global_load_lds_dwordx4 v[214:215], off
	v_lshl_add_u64 v[214:215], s[8:9], 0, v[194:195]
	s_mov_b32 m0, s62
	s_nop 0
	global_load_lds_dwordx4 v[214:215], off
	s_waitcnt vmcnt(8)
	s_waitcnt lgkmcnt(0)
	s_barrier
	s_setprio 1
	s_waitcnt lgkmcnt(0)
	v_mfma_f32_16x16x32_bf16 v[124:127], v[134:137], v[166:169], v[124:127]
	v_mfma_f32_16x16x32_bf16 v[0:3], v[142:145], v[166:169], v[0:3]
	v_mfma_f32_16x16x32_bf16 v[120:123], v[134:137], v[174:177], v[120:123]
	v_mfma_f32_16x16x32_bf16 v[116:119], v[142:145], v[174:177], v[116:119]
	v_mfma_f32_16x16x32_bf16 v[112:115], v[134:137], v[230:233], v[112:115]
	v_mfma_f32_16x16x32_bf16 v[108:111], v[142:145], v[230:233], v[108:111]
	v_mfma_f32_16x16x32_bf16 v[104:107], v[134:137], v[238:241], v[104:107]
	v_mfma_f32_16x16x32_bf16 v[4:7], v[142:145], v[238:241], v[4:7]
	v_mfma_f32_16x16x32_bf16 v[124:127], v[138:141], v[170:173], v[124:127]
	v_mfma_f32_16x16x32_bf16 v[0:3], v[146:149], v[170:173], v[0:3]
	v_mfma_f32_16x16x32_bf16 v[120:123], v[138:141], v[178:181], v[120:123]
	v_mfma_f32_16x16x32_bf16 v[116:119], v[146:149], v[178:181], v[116:119]
	v_mfma_f32_16x16x32_bf16 v[112:115], v[138:141], v[234:237], v[112:115]
	v_mfma_f32_16x16x32_bf16 v[108:111], v[146:149], v[234:237], v[108:111]
	v_mfma_f32_16x16x32_bf16 v[104:107], v[138:141], v[242:245], v[104:107]
	v_mfma_f32_16x16x32_bf16 v[4:7], v[146:149], v[242:245], v[4:7]
	s_setprio 0
	s_setprio 1
	v_mfma_f32_16x16x32_bf16 v[100:103], v[150:153], v[166:169], v[100:103]
	v_mfma_f32_16x16x32_bf16 v[96:99], v[158:161], v[166:169], v[96:99]
	v_mfma_f32_16x16x32_bf16 v[92:95], v[150:153], v[174:177], v[92:95]
	v_mfma_f32_16x16x32_bf16 v[88:91], v[158:161], v[174:177], v[88:91]
	v_mfma_f32_16x16x32_bf16 v[84:87], v[150:153], v[230:233], v[84:87]
	v_mfma_f32_16x16x32_bf16 v[80:83], v[158:161], v[230:233], v[80:83]
	v_mfma_f32_16x16x32_bf16 v[76:79], v[150:153], v[238:241], v[76:79]
	v_mfma_f32_16x16x32_bf16 v[72:75], v[158:161], v[238:241], v[72:75]
	v_mfma_f32_16x16x32_bf16 v[100:103], v[154:157], v[170:173], v[100:103]
	v_mfma_f32_16x16x32_bf16 v[96:99], v[162:165], v[170:173], v[96:99]
	v_mfma_f32_16x16x32_bf16 v[92:95], v[154:157], v[178:181], v[92:95]
	v_mfma_f32_16x16x32_bf16 v[88:91], v[162:165], v[178:181], v[88:91]
	v_mfma_f32_16x16x32_bf16 v[84:87], v[154:157], v[234:237], v[84:87]
	v_mfma_f32_16x16x32_bf16 v[80:83], v[162:165], v[234:237], v[80:83]
	v_mfma_f32_16x16x32_bf16 v[76:79], v[154:157], v[242:245], v[76:79]
	v_mfma_f32_16x16x32_bf16 v[72:75], v[162:165], v[242:245], v[72:75]
	s_setprio 0
	s_barrier
; #define PG8_STAGE(bufoff, gbase, voff) do { _Pragma("unroll") for (int _i = 0; _i < 2; ++_i) \
;         __builtin_amdgcn_global_load_lds((const unsigned*)((const char*)(gbase) + (voff)[_i]), (LAS unsigned*)(lds + (bufoff) + ldsw + _i * 8192), 16, 0, 0); } while (0)
; #define PG8_LDA(dst, b, h) do { _Pragma("unroll") for (int m = 0; m < 4; ++m) _Pragma("unroll") for (int k = 0; k < 2; ++k) dst[m][k] = *(const LAS bf16x8*)(lds + PG8_SA(b, h) + aoff + m * 2048 + k * 1024); } while (0)
; #define PG8_MMA(ai, bj, At, Bt) do { __builtin_amdgcn_s_setprio(1); _Pragma("unroll") for (int m = 0; m < 4; ++m) _Pragma("unroll") for (int n = 0; n < 2; ++n) _Pragma("unroll") for (int k = 0; k < 2; ++k) \
;         acc[ai][bj][m][n] = __builtin_amdgcn_mfma_f32_16x16x32_bf16(Bt[n][k], At[m][k], acc[ai][bj][m][n], 0, 0, 0); __builtin_amdgcn_s_setprio(0); } while (0)
; #define PG8_WAIT_V(n) asm volatile("s_waitcnt vmcnt(" #n ")" ::: "memory")
; #define PG8_WAIT_L(n) asm volatile("s_waitcnt lgkmcnt(" #n ")" ::: "memory")
; #define PG8_BAR __builtin_amdgcn_s_barrier()
; #define PG8_SCHED __builtin_amdgcn_sched_barrier(0)
;     ...
;             PG8_WAIT_V(8); PG8_WAIT_L(0); PG8_BAR; PG8_MMA(0, 0, At, B0); PG8_MMA(0, 1, At, B1); PG8_BAR; PG8_SCHED;
;             PG8_LDA(At, 1, 1); PG8_STAGE(PG8_SB(1, 0), b3, voffB); PG8_STAGE(PG8_SB(1, 1), b3 + hstepB, voffB); PG8_STAGE(PG8_SA(1, 0), a3, voffA);
;             PG8_WAIT_V(8); PG8_WAIT_L(0); PG8_BAR; PG8_MMA(1, 0, At, B0); PG8_MMA(1, 1, At, B1); PG8_BAR; PG8_SCHED;
;         }
;         if (wr == 0) PG8_BAR;
	s_add_i32 s8, s26, s11
	v_lshl_add_u64 v[212:213], v[212:213], 0, s[70:71]
	s_mov_b32 m0, s8
	ds_read_b128 v[166:169], v227 offset:49152
	ds_read_b128 v[170:173], v227 offset:50176
	ds_read_b128 v[174:177], v227 offset:51200
	ds_read_b128 v[178:181], v227 offset:52224
	ds_read_b128 v[230:233], v227 offset:53248
	ds_read_b128 v[234:237], v227 offset:54272
	ds_read_b128 v[238:241], v227 offset:55296
	ds_read_b128 v[242:245], v227 offset:56320
	global_load_lds_dwordx4 v[212:213], off
	v_lshl_add_u64 v[212:213], v[218:219], 0, s[70:71]
	s_add_i32 m0, s8, 0x2000
	s_add_i32 s8, s27, s11
	global_load_lds_dwordx4 v[212:213], off
	v_lshl_add_u64 v[212:213], v[246:247], 0, s[70:71]
	s_mov_b32 m0, s8
	v_lshl_add_u64 v[204:205], v[204:205], 0, s[70:71]
	global_load_lds_dwordx4 v[212:213], off
	s_add_i32 m0, s8, 0x2000
	s_nop 0
	global_load_lds_dwordx4 v[204:205], off
	v_lshl_add_u64 v[204:205], v[248:249], 0, s[70:71]
	s_mov_b32 m0, s65
	s_nop 0
	global_load_lds_dwordx4 v[204:205], off
	v_lshl_add_u64 v[204:205], v[250:251], 0, s[70:71]
	s_mov_b32 m0, s49
	s_nop 0
	global_load_lds_dwordx4 v[204:205], off
	s_waitcnt vmcnt(8)
	s_waitcnt lgkmcnt(0)
	s_barrier
	s_setprio 1
	s_waitcnt lgkmcnt(0)
	v_mfma_f32_16x16x32_bf16 v[68:71], v[134:137], v[166:169], v[68:71]
	v_mfma_f32_16x16x32_bf16 v[8:11], v[142:145], v[166:169], v[8:11]
	v_mfma_f32_16x16x32_bf16 v[64:67], v[134:137], v[174:177], v[64:67]
	v_mfma_f32_16x16x32_bf16 v[60:63], v[142:145], v[174:177], v[60:63]
	v_mfma_f32_16x16x32_bf16 v[56:59], v[134:137], v[230:233], v[56:59]
	v_mfma_f32_16x16x32_bf16 v[52:55], v[142:145], v[230:233], v[52:55]
	v_mfma_f32_16x16x32_bf16 v[48:51], v[134:137], v[238:241], v[48:51]
	v_mfma_f32_16x16x32_bf16 v[12:15], v[142:145], v[238:241], v[12:15]
	v_mfma_f32_16x16x32_bf16 v[68:71], v[138:141], v[170:173], v[68:71]
	v_mfma_f32_16x16x32_bf16 v[8:11], v[146:149], v[170:173], v[8:11]
	v_mfma_f32_16x16x32_bf16 v[64:67], v[138:141], v[178:181], v[64:67]
	v_mfma_f32_16x16x32_bf16 v[60:63], v[146:149], v[178:181], v[60:63]
	v_mfma_f32_16x16x32_bf16 v[56:59], v[138:141], v[234:237], v[56:59]
	v_mfma_f32_16x16x32_bf16 v[52:55], v[146:149], v[234:237], v[52:55]
	v_mfma_f32_16x16x32_bf16 v[48:51], v[138:141], v[242:245], v[48:51]
	v_mfma_f32_16x16x32_bf16 v[12:15], v[146:149], v[242:245], v[12:15]
	s_setprio 0
	s_setprio 1
	v_mfma_f32_16x16x32_bf16 v[44:47], v[150:153], v[166:169], v[44:47]
	v_mfma_f32_16x16x32_bf16 v[40:43], v[158:161], v[166:169], v[40:43]
	v_mfma_f32_16x16x32_bf16 v[36:39], v[150:153], v[174:177], v[36:39]
	v_mfma_f32_16x16x32_bf16 v[32:35], v[158:161], v[174:177], v[32:35]
	v_mfma_f32_16x16x32_bf16 v[28:31], v[150:153], v[230:233], v[28:31]
	v_mfma_f32_16x16x32_bf16 v[24:27], v[158:161], v[230:233], v[24:27]
	v_mfma_f32_16x16x32_bf16 v[20:23], v[150:153], v[238:241], v[20:23]
	v_mfma_f32_16x16x32_bf16 v[16:19], v[158:161], v[238:241], v[16:19]
	v_mfma_f32_16x16x32_bf16 v[44:47], v[154:157], v[170:173], v[44:47]
	v_mfma_f32_16x16x32_bf16 v[40:43], v[162:165], v[170:173], v[40:43]
	v_mfma_f32_16x16x32_bf16 v[36:39], v[154:157], v[178:181], v[36:39]
	v_mfma_f32_16x16x32_bf16 v[32:35], v[162:165], v[178:181], v[32:35]
	v_mfma_f32_16x16x32_bf16 v[28:31], v[154:157], v[234:237], v[28:31]
	v_mfma_f32_16x16x32_bf16 v[24:27], v[162:165], v[234:237], v[24:27]
	v_mfma_f32_16x16x32_bf16 v[20:23], v[154:157], v[242:245], v[20:23]
	v_mfma_f32_16x16x32_bf16 v[16:19], v[162:165], v[242:245], v[16:19]
	s_setprio 0
	s_barrier
	s_add_u32 s0, s0, 0x100
	s_addc_u32 s1, s1, 0
	v_lshl_add_u64 v[130:131], v[130:131], 0, s[94:95]
	v_lshl_add_u64 v[128:129], v[128:129], 0, s[94:95]
	s_cmp_ge_u32 s38, s52
	s_mov_b32 s8, s38
	s_cbranch_scc0 .LBB0_159
	v_readlane_b32 s0, v254, 50
	v_readlane_b32 s1, v254, 51
	s_and_b64 vcc, exec, s[0:1]
	s_movk_i32 s67, 0xfe
	s_cbranch_vccz .LBB0_162
	s_barrier

;     ...
;         const bool has_next = S.next(ui + 1, nxt);
;         const char* nA = has_next ? nxt.A : cA; const char* nB = has_next ? nxt.B : cB;
;         for (int t = 0; t < nt; t += 2) {
;             const bool last = (t == nt - 2);
;             const char* a1 = cA + (size_t)(t + 1) * kstep;
;             const char* a2 = last ? nA : cA + (size_t)(t + 2) * kstep; const char* b2 = last ? nB : cB + (size_t)(t + 2) * kstep;
.LBB0_317:
	s_mov_b64 s[54:55], s[68:69]
	v_mov_b32_e32 v189, v128
	s_xor_b64 s[66:67], s[64:65], -1
	v_mov_b32_e32 v128, s55
	s_mov_b64 s[36:37], s[38:39]
	s_and_b64 s[0:1], s[64:65], exec
	v_cndmask_b32_e64 v132, v161, v128, s[64:65]
	v_mov_b32_e32 v128, s54
	s_mov_b64 s[6:7], s[56:57]
	s_mov_b64 s[14:15], s[58:59]
	s_mov_b32 s26, s19
	s_cselect_b32 s13, s37, s3
	s_cselect_b32 s56, s36, s2
	v_cndmask_b32_e64 v133, v160, v128, s[64:65]
	s_mov_b32 s38, 0
	s_mov_b64 s[0:1], 0x100
	v_mov_b64_e32 v[128:129], v[172:173]
	v_mov_b64_e32 v[130:131], v[170:171]
	s_nop 0
	s_nop 0
	s_nop 0
	s_nop 0
	s_nop 0
	s_nop 0
